# r1 tiles: tile-invariant conv/gate weights loaded once per workgroup into AGPRs instead of 33 loads per tile
# speedup vs baseline: 1.0066x; 1.0055x over previous
.LBB0_384:
	s_mov_b64 s[64:65], -1
	s_cmp_lt_i32 s90, 4
	s_cselect_b64 s[0:1], -1, 0
	s_cmp_gt_i32 s91, 3
	s_cselect_b64 s[4:5], -1, 0
	s_and_b64 s[0:1], s[0:1], s[4:5]
	s_andn2_b64 vcc, exec, s[0:1]
	s_cbranch_vccnz .LBB0_589
	s_waitcnt lgkmcnt(0)
	s_load_dword s3, s[96:97], 0x128
	s_add_u32 s6, s96, 0x128
	s_addc_u32 s7, s97, 0
	s_cmpk_gt_i32 s2, 0x9ff
	s_cbranch_scc1 .LBB0_535
	v_readlane_b32 s8, v126, 2
	v_readlane_b32 s14, v126, 8
	v_readlane_b32 s15, v126, 9
	v_readlane_b32 s12, v126, 6
	v_readlane_b32 s13, v126, 7
	s_mov_b64 s[26:27], s[14:15]
	v_readlane_b32 s9, v126, 3
	s_add_u32 s8, s26, 0x233e8000
	v_readlane_b32 s10, v126, 4
	s_addc_u32 s9, s27, 0
	v_readlane_b32 s11, v126, 5
	s_add_u32 s10, s26, 0x18c40000
	s_addc_u32 s11, s27, 0
	s_mov_b64 s[24:25], s[12:13]
	s_add_u32 s12, s26, 0x18ebc000
	s_addc_u32 s13, s27, 0
	s_add_u32 s14, s26, 0x213e8000
	s_addc_u32 s15, s27, 0
	s_add_u32 s16, s26, 0x223e8000
	s_addc_u32 s17, s27, 0
	s_add_u32 s18, s26, 0x18ec8000
	s_addc_u32 s19, s27, 0
	s_add_u32 s20, s26, 0x22be8000
	s_addc_u32 s21, s27, 0
	s_add_u32 s22, s26, 0x18f48000
	s_addc_u32 s23, s27, 0
	s_add_u32 s24, s26, 0x253e8000
	v_mbcnt_lo_u32_b32 v0, -1, 0
	s_addc_u32 s25, s27, 0
	v_mov_b32_e32 v73, 0
	s_mov_b64 s[26:27], 0
	s_movk_i32 s36, 0x100
	s_movk_i32 s37, 0x1000
	s_movk_i32 s38, 0x104
	s_movk_i32 s39, 0x90
	s_waitcnt vmcnt(4)
	v_mov_b32_e32 v113, 0x3c088889
	s_add_i32 s40, 0, 0xd500
	s_add_i32 s41, 0, 0x6500
	s_movk_i32 s42, 0x110
	s_movk_i32 s43, 0xfeff
	s_mov_b32 s44, 0xff61b1e6
	v_mbcnt_hi_u32_b32 v80, -1, v0
	v_mov_b32_e32 v81, 0xf149f2ca
	s_mov_b32 s45, s2
	s_waitcnt vmcnt(3)
	v_mov_b32_e32 v115, 0
	s_waitcnt vmcnt(1)
	v_mov_b32_e32 v124, 0
	v_mov_b32_e32 v125, 0
	v_accvgpr_write_b32 a40, 0
	v_accvgpr_write_b32 a41, 0
	v_accvgpr_write_b32 a42, 0
	s_branch .LBB0_389

.LBB0_416:
	v_mov_b32_e32 v89, v77
	v_mov_b32_e32 v1, v73
	v_and_b32_e32 v82, 63, v89
	v_or_b32_e32 v0, v82, v74
	v_lshlrev_b64 v[0:1], 2, v[0:1]
	v_readlane_b32 s80, v126, 31
	v_lshl_add_u64 v[2:3], s[62:63], 0, v[0:1]
	v_readlane_b32 s81, v126, 32
	v_add_co_u32_e32 v4, vcc, s37, v2
	s_nop 0
	v_lshl_add_u64 v[0:1], s[80:81], 0, v[0:1]
	v_addc_co_u32_e32 v5, vcc, 0, v3, vcc
	s_mov_b64 exec, s[64:65]
	global_load_dword a43, v[0:1], off
	global_load_dword a44, v[2:3], off
	global_load_dword a45, v[2:3], off offset:2048
	global_load_dword a46, v[4:5], off
	global_load_dword a47, v[4:5], off offset:2048
	s_mov_b64 exec, -1
	v_ashrrev_i32_e32 v90, 6, v89
	v_and_b32_e32 v103, 1, v90
	v_and_b32_e32 v97, 15, v89
	v_lshlrev_b32_e32 v6, 10, v103
	v_or3_b32 v2, v6, v74, v97
	v_and_b32_e32 v72, 48, v89
	v_lshlrev_b32_e32 v3, 9, v103
	v_lshl_add_u64 v[0:1], s[10:11], 0, v[72:73]
	v_or3_b32 v4, v3, v74, v97
	v_lshlrev_b32_e32 v2, 7, v2
	v_mov_b32_e32 v3, v73
	v_lshl_add_u64 v[0:1], v[0:1], 0, v[2:3]
	s_mov_b32 s0, 0x10000
	v_add_co_u32_e32 v2, vcc, s0, v0
	s_mov_b32 s0, 0x11000
	s_nop 0
	v_addc_co_u32_e32 v3, vcc, 0, v1, vcc
	v_add_co_u32_e32 v6, vcc, s0, v0
	v_mov_b32_e32 v5, v73
	s_nop 0
	v_addc_co_u32_e32 v7, vcc, 0, v1, vcc
	v_add_co_u32_e32 v12, vcc, s37, v0
	v_readlane_b32 s84, v126, 35
	v_readlane_b32 s85, v126, 36
	v_readlane_b32 s88, v126, 39
	v_readlane_b32 s89, v126, 40
	s_mov_b64 exec, s[64:65]
	global_load_dwordx4 a[52:55], v[0:1], off
	global_load_dwordx4 a[56:59], v[0:1], off offset:64
	s_mov_b64 exec, -1
	v_lshlrev_b64 v[8:9], 2, v[4:5]
	s_mov_b64 exec, s[64:65]
	global_load_dwordx4 a[60:63], v[2:3], off offset:64
	global_load_dwordx4 a[64:67], v[2:3], off offset:2048
	global_load_dwordx4 a[68:71], v[0:1], off offset:2048
	global_load_dwordx4 a[72:75], v[0:1], off offset:2112
	global_load_dwordx4 a[76:79], v[2:3], off offset:2112
	s_mov_b64 exec, -1
	v_or_b32_e32 v2, 16, v4
	v_mov_b32_e32 v3, v73
	v_addc_co_u32_e32 v13, vcc, 0, v1, vcc
	v_or_b32_e32 v0, 32, v4
	v_mov_b32_e32 v1, v73
	v_or_b32_e32 v4, 48, v4
	v_lshl_add_u64 v[32:33], s[84:85], 0, v[8:9]
	v_lshl_add_u64 v[34:35], s[88:89], 0, v[8:9]
	v_lshl_add_u64 v[8:9], s[12:13], 0, v[8:9]
	v_lshl_add_u64 v[2:3], v[2:3], 2, s[12:13]
	v_lshl_add_u64 v[14:15], v[0:1], 2, s[12:13]
	v_lshl_add_u64 v[4:5], v[4:5], 2, s[12:13]
	s_mov_b64 exec, s[64:65]
	global_load_dword a48, v[8:9], off
	global_load_dword a49, v[2:3], off
	global_load_dwordx4 a[80:83], v[12:13], off
	global_load_dwordx4 a[84:87], v[6:7], off offset:-4096
	global_load_dwordx4 a[88:91], v[6:7], off
	global_load_dwordx4 a[92:95], v[12:13], off offset:64
	s_mov_b64 exec, -1
	s_nop 0
	s_mov_b64 exec, s[64:65]
	global_load_dwordx4 a[96:99], v[12:13], off offset:2048
	global_load_dwordx4 a[100:103], v[6:7], off offset:64
	global_load_dwordx4 a[104:107], v[6:7], off offset:2048
	global_load_dword a50, v[14:15], off
	global_load_dword a51, v[4:5], off
	s_mov_b64 exec, -1
	s_nop 0
	s_mov_b64 exec, s[64:65]
	global_load_dwordx4 a[108:111], v[12:13], off offset:2112
	s_mov_b64 exec, -1
	s_nop 0
	s_mov_b64 exec, s[64:65]
	global_load_dwordx4 a[112:115], v[6:7], off offset:2112
	s_mov_b64 exec, -1
	s_nop 0
	s_mov_b64 exec, s[64:65]
	global_load_dword a116, v[32:33], off
	global_load_dword a117, v[32:33], off offset:64
	global_load_dword a118, v[32:33], off offset:128
	global_load_dword a119, v[32:33], off offset:192
	global_load_dword a120, v[34:35], off
	global_load_dword a121, v[34:35], off offset:64
	global_load_dword a122, v[34:35], off offset:128
	global_load_dword a123, v[34:35], off offset:192
	s_mov_b64 exec, -1
	v_lshlrev_b32_e32 v33, 16, v88
	v_and_b32_e32 v35, 0xffff0000, v88
	v_lshlrev_b32_e32 v79, 16, v87
	v_and_b32_e32 v105, 0xffff0000, v87
	v_lshl_add_u32 v32, v82, 2, 0
	s_movk_i32 s0, 0x820
	v_lshlrev_b32_e32 v34, 1, v82
	v_sub_u32_e32 v34, v32, v34
	v_lshlrev_b32_e32 v106, 16, v86
	v_and_b32_e32 v107, 0xffff0000, v86
	v_lshlrev_b32_e32 v108, 16, v85
	v_and_b32_e32 v109, 0xffff0000, v85
	v_lshlrev_b32_e32 v110, 16, v84
	v_and_b32_e32 v111, 0xffff0000, v84
	v_lshlrev_b32_e32 v112, 16, v83
	s_waitcnt lgkmcnt(0)
	s_cmp_eq_u64 s[64:65], 0
	s_cbranch_scc1 .Lr1w_have
	s_waitcnt vmcnt(0)
.Lr1w_have:
	v_accvgpr_read_b32 v38, a43
	v_accvgpr_read_b32 v39, a44
	v_accvgpr_read_b32 v75, a45
	v_accvgpr_read_b32 v76, a46
	v_accvgpr_read_b32 v78, a47
	v_accvgpr_read_b32 v64, a52
	v_accvgpr_read_b32 v65, a53
	v_accvgpr_read_b32 v66, a54
	v_accvgpr_read_b32 v67, a55
	v_accvgpr_read_b32 v60, a56
	v_accvgpr_read_b32 v61, a57
	v_accvgpr_read_b32 v62, a58
	v_accvgpr_read_b32 v63, a59
	v_accvgpr_read_b32 v56, a60
	v_accvgpr_read_b32 v57, a61
	v_accvgpr_read_b32 v58, a62
	v_accvgpr_read_b32 v59, a63
	v_accvgpr_read_b32 v44, a64
	v_accvgpr_read_b32 v45, a65
	v_accvgpr_read_b32 v46, a66
	v_accvgpr_read_b32 v47, a67
	v_accvgpr_read_b32 v52, a68
	v_accvgpr_read_b32 v53, a69
	v_accvgpr_read_b32 v54, a70
	v_accvgpr_read_b32 v55, a71
	v_accvgpr_read_b32 v48, a72
	v_accvgpr_read_b32 v49, a73
	v_accvgpr_read_b32 v50, a74
	v_accvgpr_read_b32 v51, a75
	v_accvgpr_read_b32 v40, a76
	v_accvgpr_read_b32 v41, a77
	v_accvgpr_read_b32 v42, a78
	v_accvgpr_read_b32 v43, a79
	v_accvgpr_read_b32 v102, a48
	v_accvgpr_read_b32 v99, a49
	v_accvgpr_read_b32 v24, a80
	v_accvgpr_read_b32 v25, a81
	v_accvgpr_read_b32 v26, a82
	v_accvgpr_read_b32 v27, a83
	v_accvgpr_read_b32 v68, a84
	v_accvgpr_read_b32 v69, a85
	v_accvgpr_read_b32 v70, a86
	v_accvgpr_read_b32 v71, a87
	v_accvgpr_read_b32 v16, a88
	v_accvgpr_read_b32 v17, a89
	v_accvgpr_read_b32 v18, a90
	v_accvgpr_read_b32 v19, a91
	v_accvgpr_read_b32 v28, a92
	v_accvgpr_read_b32 v29, a93
	v_accvgpr_read_b32 v30, a94
	v_accvgpr_read_b32 v31, a95
	v_accvgpr_read_b32 v8, a96
	v_accvgpr_read_b32 v9, a97
	v_accvgpr_read_b32 v10, a98
	v_accvgpr_read_b32 v11, a99
	v_accvgpr_read_b32 v20, a100
	v_accvgpr_read_b32 v21, a101
	v_accvgpr_read_b32 v22, a102
	v_accvgpr_read_b32 v23, a103
	v_accvgpr_read_b32 v0, a104
	v_accvgpr_read_b32 v1, a105
	v_accvgpr_read_b32 v2, a106
	v_accvgpr_read_b32 v3, a107
	v_accvgpr_read_b32 v95, a50
	v_accvgpr_read_b32 v92, a51
	v_accvgpr_read_b32 v12, a108
	v_accvgpr_read_b32 v13, a109
	v_accvgpr_read_b32 v14, a110
	v_accvgpr_read_b32 v15, a111
	v_accvgpr_read_b32 v4, a112
	v_accvgpr_read_b32 v5, a113
	v_accvgpr_read_b32 v6, a114
	v_accvgpr_read_b32 v7, a115
	v_accvgpr_read_b32 v104, a116
	v_accvgpr_read_b32 v100, a117
	v_accvgpr_read_b32 v96, a118
	v_accvgpr_read_b32 v93, a119
	v_accvgpr_read_b32 v101, a120
	v_accvgpr_read_b32 v98, a121
	v_accvgpr_read_b32 v94, a122
	v_accvgpr_read_b32 v91, a123
	s_mov_b64 s[64:65], 0
	s_add_i32 s4, s34, s3
	s_cmpk_lt_i32 s4, 0x800
	v_readlane_b32 s82, v126, 33
	v_readlane_b32 s83, v126, 34
	v_readlane_b32 s86, v126, 37
	v_readlane_b32 s87, v126, 38
	v_readlane_b32 s90, v126, 41
	v_readlane_b32 s91, v126, 42
	v_readlane_b32 s92, v126, 43
	v_readlane_b32 s93, v126, 44
	v_readlane_b32 s94, v126, 45
	v_readlane_b32 s95, v126, 46
	s_waitcnt vmcnt(31)
	v_fma_f32 v33, v39, v33, v38
	s_waitcnt vmcnt(30)
	v_fmac_f32_e32 v33, v75, v35
	s_waitcnt vmcnt(29)
	v_fmac_f32_e32 v33, v76, v79
	s_waitcnt vmcnt(28)
	v_fmac_f32_e32 v33, v78, v105
	v_mad_u64_u32 v[36:37], s[0:1], v90, s0, v[32:33]
	s_movk_i32 s0, 0x480
	ds_write_b32 v36, v33
	v_mad_u64_u32 v[36:37], s[0:1], v90, s0, v[34:35]
	v_fma_f32 v35, v39, v35, v38
	v_fmac_f32_e32 v35, v75, v79
	v_cvt_pk_bf16_f32 v33, v33, v73
	ds_write_b16 v36, v33 offset:16640
	v_fmac_f32_e32 v35, v76, v105
	v_lshl_or_b32 v36, v90, 3, 1
	v_fmac_f32_e32 v35, v78, v106
	v_mad_u64_u32 v[32:33], s[0:1], v36, s38, v[32:33]
	ds_write_b32 v32, v35
	v_cvt_pk_bf16_f32 v33, v35, v73
	v_mad_u64_u32 v[34:35], s[0:1], v36, s39, v[34:35]
	ds_write_b16 v34, v33 offset:16640
	v_fma_f32 v33, v39, v79, v38
	v_fmac_f32_e32 v33, v75, v105
	v_fmac_f32_e32 v33, v76, v106
	v_fmac_f32_e32 v33, v78, v107
	ds_write_b32 v32, v33 offset:260
	v_cvt_pk_bf16_f32 v33, v33, v73
	ds_write_b16 v34, v33 offset:16784
	v_fma_f32 v33, v39, v105, v38
	v_fmac_f32_e32 v33, v75, v106
	v_fmac_f32_e32 v33, v76, v107
	v_fmac_f32_e32 v33, v78, v108
	ds_write_b32 v32, v33 offset:520
	v_cvt_pk_bf16_f32 v33, v33, v73
	ds_write_b16 v34, v33 offset:16928
	v_fma_f32 v33, v39, v106, v38
	v_fmac_f32_e32 v33, v75, v107
	v_fmac_f32_e32 v33, v76, v108
	v_fmac_f32_e32 v33, v78, v109
	ds_write_b32 v32, v33 offset:780
	v_cvt_pk_bf16_f32 v33, v33, v73
	ds_write_b16 v34, v33 offset:17072
	v_fma_f32 v33, v39, v107, v38
	v_fmac_f32_e32 v33, v75, v108
	v_fmac_f32_e32 v33, v76, v109
	v_fmac_f32_e32 v33, v78, v110
	ds_write_b32 v32, v33 offset:1040
	v_cvt_pk_bf16_f32 v33, v33, v73
	ds_write_b16 v34, v33 offset:17216
	v_fma_f32 v33, v39, v108, v38
	v_fmac_f32_e32 v38, v39, v109
	v_fmac_f32_e32 v33, v75, v109
	v_fmac_f32_e32 v38, v75, v110
	v_fmac_f32_e32 v33, v76, v110
	v_fmac_f32_e32 v38, v76, v111
	v_fmac_f32_e32 v33, v78, v111
	v_fmac_f32_e32 v38, v78, v112
	ds_write_b32 v32, v33 offset:1300
	v_cvt_pk_bf16_f32 v33, v33, v73
	ds_write_b16 v34, v33 offset:17360
	ds_write_b32 v32, v38 offset:1560
	v_cvt_pk_bf16_f32 v32, v38, v73
	s_mov_b64 s[0:1], -1
	v_ashrrev_i32_e32 v38, 3, v89
	ds_write_b16 v34, v32 offset:17504
	s_cbranch_scc1 .LBB0_418
	v_ashrrev_i32_e32 v32, 3, v89
	s_mov_b64 s[0:1], 0
